# EpiQkvA epilogue hand-written with in-loop row-scale preload (on top of EpiUq + EpiKvB)
# speedup vs baseline: 1.0157x; 1.0089x over previous
.LBB0_268:
	s_add_u32 s24, s2, 0x100
	s_addc_u32 s25, s3, 0
	s_add_i32 s0, 0, 0x10000
	s_cmp_eq_u32 s44, 2
	s_cselect_b32 s41, s19, s25
	s_cselect_b32 s40, s18, s24
	v_add_u32_e32 v0, s0, v178
	s_cselect_b32 s39, s79, s43
	s_cselect_b32 s38, s78, s42
	s_add_i32 s45, 0, 0x14000
	ds_read_b128 v[50:53], v0
	ds_read_b128 v[54:57], v0 offset:1024
	ds_read_b128 v[150:153], v0 offset:2048
	ds_read_b128 v[154:157], v0 offset:3072
	v_add_u32_e32 v0, s45, v178
	ds_read_b128 v[158:161], v0
	ds_read_b128 v[162:165], v0 offset:1024
	ds_read_b128 v[166:169], v0 offset:2048
	ds_read_b128 v[170:173], v0 offset:3072
	s_cmp_eq_u32 s44, 2
	s_cbranch_scc0 .Luq_pa_skip
	v_and_b32_e32 v253, 15, v193
	v_lshl_add_u32 v252, s29, 8, v253
	v_add_u32_e32 v252, s82, v252
	v_bfe_u32 v253, v193, 4, 2
	v_lshlrev_b32_e32 v253, 4, v253
	v_mul_u32_u24_e32 v252, 0x60, v252
	v_add_u32_e32 v252, v252, v253
	global_load_dwordx4 v[194:197], v252, s[16:17]
	global_load_dwordx4 v[198:201], v252, s[16:17] offset:1536
	global_load_dwordx4 v[202:205], v252, s[16:17] offset:3072
	v_add_u32_e32 v253, 0x1200, v252
	global_load_dwordx4 v[206:209], v253, s[16:17]

.LBB0_354:
	s_add_u32 s0, s42, s72
	s_addc_u32 s63, s43, s73
	s_add_u32 s66, s0, 0x100
	s_addc_u32 s67, s63, 0
	s_and_b64 s[64:65], s[44:45], exec
	s_cselect_b32 s75, s19, s67
	s_cselect_b32 s74, s18, s66
	s_add_u32 s64, s40, s72
	s_addc_u32 s65, s41, s73
	s_add_u32 s64, s64, 0x100
	s_addc_u32 s65, s65, 0
	s_add_i32 s66, 0, 0x10000
	s_and_b64 s[44:45], s[44:45], exec
	s_cselect_b32 s77, s17, s65
	s_cselect_b32 s76, s91, s64
	s_add_i32 s31, 0, 0x14000
	s_add_u32 vcc_lo, s0, 0x30080
	s_addc_u32 vcc_hi, s63, 0
	s_add_i32 s63, s66, s54
	s_add_i32 m0, s34, 0xc000
	s_add_i32 s55, s34, 0xe000
	s_add_i32 s30, s63, 0x2000
	v_add_u32_e32 v0, s66, v148
	s_add_u32 s78, s76, 0x10000
	ds_read_b128 v[130:133], v0
	ds_read_b128 v[144:147], v0 offset:1024
	ds_read_b128 v[150:153], v0 offset:2048
	ds_read_b128 v[154:157], v0 offset:3072
	v_add_u32_e32 v0, s31, v148
	s_addc_u32 s79, s77, 0
	s_add_i32 s67, s31, s54
	ds_read_b128 v[158:161], v0
	ds_read_b128 v[162:165], v0 offset:1024
	ds_read_b128 v[166:169], v0 offset:2048
	ds_read_b128 v[170:173], v0 offset:3072
	s_add_i32 s0, s67, 0x2000
	s_add_i32 s95, 0, 0x18000
	s_add_i32 s94, 0, 0x1c000
	s_add_u32 s72, s74, 0x30000
	s_addc_u32 s73, s75, 0
	s_add_i32 s93, s95, s54
	s_add_i32 s92, s93, 0x2000
	s_add_u32 s44, s76, 0x10080
	s_addc_u32 s45, s77, 0
	s_add_i32 s65, s94, s54
	s_add_i32 s64, s65, 0x2000
	s_cmp_eq_u64 s[38:39], 0
	s_cbranch_scc0 .Lkvb_pa_skip
	v_and_b32_e32 v253, 15, v193
	v_lshl_add_u32 v252, s90, 8, v253
	v_add_u32_e32 v252, s82, v252
	v_bfe_u32 v253, v193, 4, 2
	v_lshlrev_b32_e32 v253, 4, v253
	v_mul_u32_u24_e32 v252, 0x60, v252
	v_add_u32_e32 v252, v252, v253
	global_load_dwordx4 v[194:197], v252, s[10:11]
	global_load_dwordx4 v[198:201], v252, s[10:11] offset:1536
	global_load_dwordx4 v[202:205], v252, s[10:11] offset:3072
	v_add_u32_e32 v253, 0x1200, v252
	global_load_dwordx4 v[206:209], v253, s[10:11]

.LBB0_623:
	s_add_u32 s0, s24, 0xfffc0080
	s_addc_u32 s38, s25, -1
	s_add_i32 s63, 0, 0x10000
	s_cmp_eq_u32 s74, 12
	s_cselect_b32 s41, s19, s38
	s_cselect_b32 s40, s42, s0
	v_add_u32_e32 v0, s63, v176
	s_cselect_b32 s39, s17, s55
	s_cselect_b32 s38, s43, s54
	s_add_i32 s0, 0, 0x14000
	ds_read_b128 v[142:145], v0
	ds_read_b128 v[146:149], v0 offset:1024
	ds_read_b128 v[150:153], v0 offset:2048
	ds_read_b128 v[154:157], v0 offset:3072
	v_add_u32_e32 v0, s0, v176
	ds_read_b128 v[158:161], v0
	ds_read_b128 v[162:165], v0 offset:1024
	ds_read_b128 v[166:169], v0 offset:2048
	ds_read_b128 v[170:173], v0 offset:3072
	s_cmp_eq_u32 s74, 12
	s_cbranch_scc0 .Lqkv_pa_skip
	v_and_b32_e32 v253, 15, v193
	v_lshl_add_u32 v252, s29, 8, v253
	v_add_u32_e32 v252, s87, v252
	v_bfe_u32 v253, v193, 4, 2
	v_lshlrev_b32_e32 v253, 4, v253
	v_mul_u32_u24_e32 v252, 0x40, v252
	v_add_u32_e32 v252, v252, v253
	global_load_dwordx4 v[194:197], v252, s[12:13]
	global_load_dwordx4 v[198:201], v252, s[12:13] offset:1024
	global_load_dwordx4 v[202:205], v252, s[12:13] offset:2048
	global_load_dwordx4 v[206:209], v252, s[12:13] offset:3072
.Lqkv_pa_skip:
	v_lshl_add_u64 v[174:175], s[24:25], 0, v[140:141]
	s_add_i32 m0, s83, 0xc000
	ds_read_b128 v[178:181], v177
	ds_read_b128 v[182:185], v177 offset:1024
	ds_read_b128 v[186:189], v177 offset:2048
	ds_read_b128 v[214:217], v177 offset:3072
	ds_read_b128 v[228:231], v177 offset:4096
	ds_read_b128 v[232:235], v177 offset:5120
	ds_read_b128 v[236:239], v177 offset:6144
	ds_read_b128 v[240:243], v177 offset:7168
	global_load_lds_dwordx4 v[174:175], off
	v_lshl_add_u64 v[174:175], s[24:25], 0, v[138:139]
	s_add_i32 m0, s83, 0xe000
	s_nop 0
	global_load_lds_dwordx4 v[174:175], off
	s_waitcnt vmcnt(8)
	s_waitcnt lgkmcnt(0)
	s_barrier
	s_setprio 1
	s_waitcnt lgkmcnt(0)
	v_mfma_f32_16x16x32_bf16 v[126:129], v[142:145], v[178:181], v[126:129]
	v_mfma_f32_16x16x32_bf16 v[122:125], v[150:153], v[178:181], v[122:125]
	v_mfma_f32_16x16x32_bf16 v[110:113], v[142:145], v[186:189], v[110:113]
	v_mfma_f32_16x16x32_bf16 v[106:109], v[150:153], v[186:189], v[106:109]
	v_mfma_f32_16x16x32_bf16 v[94:97], v[142:145], v[228:231], v[94:97]
	v_mfma_f32_16x16x32_bf16 v[90:93], v[150:153], v[228:231], v[90:93]
	v_mfma_f32_16x16x32_bf16 v[78:81], v[142:145], v[236:239], v[78:81]
	v_mfma_f32_16x16x32_bf16 v[74:77], v[150:153], v[236:239], v[74:77]
	v_mfma_f32_16x16x32_bf16 v[126:129], v[146:149], v[182:185], v[126:129]
	v_mfma_f32_16x16x32_bf16 v[122:125], v[154:157], v[182:185], v[122:125]
	v_mfma_f32_16x16x32_bf16 v[110:113], v[146:149], v[214:217], v[110:113]
	v_mfma_f32_16x16x32_bf16 v[106:109], v[154:157], v[214:217], v[106:109]
	v_mfma_f32_16x16x32_bf16 v[94:97], v[146:149], v[232:235], v[94:97]
	v_mfma_f32_16x16x32_bf16 v[90:93], v[154:157], v[232:235], v[90:93]
	v_mfma_f32_16x16x32_bf16 v[78:81], v[146:149], v[240:243], v[78:81]
	v_mfma_f32_16x16x32_bf16 v[74:77], v[154:157], v[240:243], v[74:77]
	s_setprio 0
	s_setprio 1
	v_mfma_f32_16x16x32_bf16 v[118:121], v[158:161], v[178:181], v[118:121]
	v_mfma_f32_16x16x32_bf16 v[114:117], v[166:169], v[178:181], v[114:117]
	v_mfma_f32_16x16x32_bf16 v[102:105], v[158:161], v[186:189], v[102:105]
	v_mfma_f32_16x16x32_bf16 v[98:101], v[166:169], v[186:189], v[98:101]
	v_mfma_f32_16x16x32_bf16 v[86:89], v[158:161], v[228:231], v[86:89]
	v_mfma_f32_16x16x32_bf16 v[82:85], v[166:169], v[228:231], v[82:85]
	v_mfma_f32_16x16x32_bf16 v[70:73], v[158:161], v[236:239], v[70:73]
	v_mfma_f32_16x16x32_bf16 v[66:69], v[166:169], v[236:239], v[66:69]
	v_mfma_f32_16x16x32_bf16 v[118:121], v[162:165], v[182:185], v[118:121]
	v_mfma_f32_16x16x32_bf16 v[114:117], v[170:173], v[182:185], v[114:117]
	v_mfma_f32_16x16x32_bf16 v[102:105], v[162:165], v[214:217], v[102:105]
	v_mfma_f32_16x16x32_bf16 v[98:101], v[170:173], v[214:217], v[98:101]
	v_mfma_f32_16x16x32_bf16 v[86:89], v[162:165], v[232:235], v[86:89]
	v_mfma_f32_16x16x32_bf16 v[82:85], v[170:173], v[232:235], v[82:85]
	v_mfma_f32_16x16x32_bf16 v[70:73], v[162:165], v[240:243], v[70:73]
	v_mfma_f32_16x16x32_bf16 v[66:69], v[170:173], v[240:243], v[66:69]
	s_setprio 0
	s_barrier
	s_add_i32 s63, s63, s82
	v_lshl_add_u64 v[174:175], s[38:39], 0, v[134:135]
	s_mov_b32 m0, s63
	ds_read_b128 v[178:181], v177 offset:16384
	ds_read_b128 v[182:185], v177 offset:17408
	ds_read_b128 v[186:189], v177 offset:18432
	ds_read_b128 v[214:217], v177 offset:19456
	ds_read_b128 v[228:231], v177 offset:20480
	ds_read_b128 v[232:235], v177 offset:21504
	ds_read_b128 v[236:239], v177 offset:22528
	ds_read_b128 v[240:243], v177 offset:23552
	global_load_lds_dwordx4 v[174:175], off
	s_add_i32 m0, s63, 0x2000
	s_add_u32 s64, s38, 0x40000
	v_lshl_add_u64 v[190:191], s[38:39], 0, v[130:131]
	s_addc_u32 s65, s39, 0
	s_add_i32 s0, s0, s82
	global_load_lds_dwordx4 v[190:191], off
	v_lshl_add_u64 v[218:219], s[64:65], 0, v[134:135]
	s_mov_b32 m0, s0
	v_lshl_add_u64 v[244:245], s[40:41], 0, v[132:133]
	global_load_lds_dwordx4 v[218:219], off
	v_lshl_add_u64 v[218:219], s[64:65], 0, v[130:131]
	s_add_i32 m0, s0, 0x2000
	s_nop 0
	global_load_lds_dwordx4 v[218:219], off
	v_lshl_add_u64 v[218:219], s[40:41], 0, v[136:137]
	s_mov_b32 m0, s83
	s_nop 0
	global_load_lds_dwordx4 v[218:219], off
	s_mov_b32 m0, s84
	s_nop 0
	global_load_lds_dwordx4 v[244:245], off
	s_waitcnt vmcnt(8)
	s_waitcnt lgkmcnt(0)
	s_barrier
	s_setprio 1
	s_waitcnt lgkmcnt(0)
	v_mfma_f32_16x16x32_bf16 v[62:65], v[142:145], v[178:181], v[62:65]
	v_mfma_f32_16x16x32_bf16 v[58:61], v[150:153], v[178:181], v[58:61]
	v_mfma_f32_16x16x32_bf16 v[46:49], v[142:145], v[186:189], v[46:49]
	v_mfma_f32_16x16x32_bf16 v[42:45], v[150:153], v[186:189], v[42:45]
	v_mfma_f32_16x16x32_bf16 v[30:33], v[142:145], v[228:231], v[30:33]
	v_mfma_f32_16x16x32_bf16 v[26:29], v[150:153], v[228:231], v[26:29]
	v_mfma_f32_16x16x32_bf16 v[14:17], v[142:145], v[236:239], v[14:17]
	v_mfma_f32_16x16x32_bf16 v[10:13], v[150:153], v[236:239], v[10:13]
	v_mfma_f32_16x16x32_bf16 v[62:65], v[146:149], v[182:185], v[62:65]
	v_mfma_f32_16x16x32_bf16 v[58:61], v[154:157], v[182:185], v[58:61]
	v_mfma_f32_16x16x32_bf16 v[46:49], v[146:149], v[214:217], v[46:49]
	v_mfma_f32_16x16x32_bf16 v[42:45], v[154:157], v[214:217], v[42:45]
	v_mfma_f32_16x16x32_bf16 v[30:33], v[146:149], v[232:235], v[30:33]
	v_mfma_f32_16x16x32_bf16 v[26:29], v[154:157], v[232:235], v[26:29]
	v_mfma_f32_16x16x32_bf16 v[14:17], v[146:149], v[240:243], v[14:17]
	v_mfma_f32_16x16x32_bf16 v[10:13], v[154:157], v[240:243], v[10:13]
	s_setprio 0
	s_setprio 1
	v_mfma_f32_16x16x32_bf16 v[54:57], v[158:161], v[178:181], v[54:57]
	v_mfma_f32_16x16x32_bf16 v[50:53], v[166:169], v[178:181], v[50:53]
	v_mfma_f32_16x16x32_bf16 v[38:41], v[158:161], v[186:189], v[38:41]
	v_mfma_f32_16x16x32_bf16 v[34:37], v[166:169], v[186:189], v[34:37]
	v_mfma_f32_16x16x32_bf16 v[22:25], v[158:161], v[228:231], v[22:25]
	v_mfma_f32_16x16x32_bf16 v[18:21], v[166:169], v[228:231], v[18:21]
	v_mfma_f32_16x16x32_bf16 v[6:9], v[158:161], v[236:239], v[6:9]
	v_mfma_f32_16x16x32_bf16 v[2:5], v[166:169], v[236:239], v[2:5]
	v_mfma_f32_16x16x32_bf16 v[54:57], v[162:165], v[182:185], v[54:57]
	v_mfma_f32_16x16x32_bf16 v[50:53], v[170:173], v[182:185], v[50:53]
	v_mfma_f32_16x16x32_bf16 v[38:41], v[162:165], v[214:217], v[38:41]
	v_mfma_f32_16x16x32_bf16 v[34:37], v[170:173], v[214:217], v[34:37]
	v_mfma_f32_16x16x32_bf16 v[22:25], v[162:165], v[232:235], v[22:25]
	v_mfma_f32_16x16x32_bf16 v[18:21], v[170:173], v[232:235], v[18:21]
	v_mfma_f32_16x16x32_bf16 v[6:9], v[162:165], v[240:243], v[6:9]
	v_mfma_f32_16x16x32_bf16 v[2:5], v[170:173], v[240:243], v[2:5]
	s_setprio 0
	s_barrier
	s_add_i32 s0, 0, 0x18000
	v_add_u32_e32 v0, s0, v176
	s_add_i32 s63, 0, 0x1c000
	ds_read_b128 v[142:145], v0
	ds_read_b128 v[146:149], v0 offset:1024
	ds_read_b128 v[150:153], v0 offset:2048
	ds_read_b128 v[154:157], v0 offset:3072
	v_add_u32_e32 v0, s63, v176
	ds_read_b128 v[158:161], v0
	ds_read_b128 v[162:165], v0 offset:1024
	ds_read_b128 v[166:169], v0 offset:2048
	ds_read_b128 v[170:173], v0 offset:3072
	s_add_u32 s40, s40, 0x40000
	s_addc_u32 s41, s41, 0
	s_mov_b32 m0, s85
	v_lshl_add_u64 v[246:247], s[40:41], 0, v[136:137]
	ds_read_b128 v[178:181], v177 offset:32768
	ds_read_b128 v[182:185], v177 offset:33792
	ds_read_b128 v[186:189], v177 offset:34816
	ds_read_b128 v[214:217], v177 offset:35840
	ds_read_b128 v[228:231], v177 offset:36864
	ds_read_b128 v[232:235], v177 offset:37888
	ds_read_b128 v[236:239], v177 offset:38912
	ds_read_b128 v[240:243], v177 offset:39936
	s_cmp_eq_u32 s74, 12
	s_cbranch_scc0 .Lqkv_pb_skip
	v_add_f32_e32 v221, v195, v194
	v_add_f32_e32 v253, v196, v197
	v_add_f32_e32 v221, v221, v253
	v_add_f32_e32 v222, v199, v198
	v_add_f32_e32 v253, v200, v201
	v_add_f32_e32 v222, v222, v253
	v_add_f32_e32 v223, v203, v202
	v_add_f32_e32 v253, v204, v205
	v_add_f32_e32 v223, v223, v253
	v_add_f32_e32 v224, v207, v206
	v_add_f32_e32 v253, v208, v209
	v_add_f32_e32 v224, v224, v253
	v_add_u32_e32 v253, 0x2000, v252
	global_load_dwordx4 v[194:197], v253, s[12:13]
	global_load_dwordx4 v[198:201], v253, s[12:13] offset:1024
	global_load_dwordx4 v[202:205], v253, s[12:13] offset:2048
	global_load_dwordx4 v[206:209], v253, s[12:13] offset:3072
.Lqkv_pb_skip:
	global_load_lds_dwordx4 v[246:247], off
	v_lshl_add_u64 v[246:247], s[40:41], 0, v[132:133]
	s_mov_b32 m0, s86
	s_nop 0
	global_load_lds_dwordx4 v[246:247], off
	s_waitcnt vmcnt(8)
	s_waitcnt lgkmcnt(0)
	s_barrier
	s_setprio 1
	s_waitcnt lgkmcnt(0)
	v_mfma_f32_16x16x32_bf16 v[126:129], v[142:145], v[178:181], v[126:129]
	v_mfma_f32_16x16x32_bf16 v[122:125], v[150:153], v[178:181], v[122:125]
	v_mfma_f32_16x16x32_bf16 v[110:113], v[142:145], v[186:189], v[110:113]
	v_mfma_f32_16x16x32_bf16 v[106:109], v[150:153], v[186:189], v[106:109]
	v_mfma_f32_16x16x32_bf16 v[94:97], v[142:145], v[228:231], v[94:97]
	v_mfma_f32_16x16x32_bf16 v[90:93], v[150:153], v[228:231], v[90:93]
	v_mfma_f32_16x16x32_bf16 v[78:81], v[142:145], v[236:239], v[78:81]
	v_mfma_f32_16x16x32_bf16 v[74:77], v[150:153], v[236:239], v[74:77]
	v_mfma_f32_16x16x32_bf16 v[126:129], v[146:149], v[182:185], v[126:129]
	v_mfma_f32_16x16x32_bf16 v[122:125], v[154:157], v[182:185], v[122:125]
	v_mfma_f32_16x16x32_bf16 v[110:113], v[146:149], v[214:217], v[110:113]
	v_mfma_f32_16x16x32_bf16 v[106:109], v[154:157], v[214:217], v[106:109]
	v_mfma_f32_16x16x32_bf16 v[94:97], v[146:149], v[232:235], v[94:97]
	v_mfma_f32_16x16x32_bf16 v[90:93], v[154:157], v[232:235], v[90:93]
	v_mfma_f32_16x16x32_bf16 v[78:81], v[146:149], v[240:243], v[78:81]
	v_mfma_f32_16x16x32_bf16 v[74:77], v[154:157], v[240:243], v[74:77]
	s_setprio 0
	s_setprio 1
	v_mfma_f32_16x16x32_bf16 v[118:121], v[158:161], v[178:181], v[118:121]
	v_mfma_f32_16x16x32_bf16 v[114:117], v[166:169], v[178:181], v[114:117]
	v_mfma_f32_16x16x32_bf16 v[102:105], v[158:161], v[186:189], v[102:105]
	v_mfma_f32_16x16x32_bf16 v[98:101], v[166:169], v[186:189], v[98:101]
	v_mfma_f32_16x16x32_bf16 v[86:89], v[158:161], v[228:231], v[86:89]
	v_mfma_f32_16x16x32_bf16 v[82:85], v[166:169], v[228:231], v[82:85]
	v_mfma_f32_16x16x32_bf16 v[70:73], v[158:161], v[236:239], v[70:73]
	v_mfma_f32_16x16x32_bf16 v[66:69], v[166:169], v[236:239], v[66:69]
	v_mfma_f32_16x16x32_bf16 v[118:121], v[162:165], v[182:185], v[118:121]
	v_mfma_f32_16x16x32_bf16 v[114:117], v[170:173], v[182:185], v[114:117]
	v_mfma_f32_16x16x32_bf16 v[102:105], v[162:165], v[214:217], v[102:105]
	v_mfma_f32_16x16x32_bf16 v[98:101], v[170:173], v[214:217], v[98:101]
	v_mfma_f32_16x16x32_bf16 v[86:89], v[162:165], v[232:235], v[86:89]
	v_mfma_f32_16x16x32_bf16 v[82:85], v[170:173], v[232:235], v[82:85]
	v_mfma_f32_16x16x32_bf16 v[70:73], v[162:165], v[240:243], v[70:73]
	v_mfma_f32_16x16x32_bf16 v[66:69], v[170:173], v[240:243], v[66:69]
	s_setprio 0
	s_barrier
	s_add_i32 s0, s0, s82
	v_lshl_add_u64 v[174:175], v[174:175], 0, s[52:53]
	s_mov_b32 m0, s0
	ds_read_b128 v[178:181], v177 offset:49152
	ds_read_b128 v[182:185], v177 offset:50176
	ds_read_b128 v[186:189], v177 offset:51200
	ds_read_b128 v[214:217], v177 offset:52224
	ds_read_b128 v[228:231], v177 offset:53248
	ds_read_b128 v[232:235], v177 offset:54272
	ds_read_b128 v[236:239], v177 offset:55296
	ds_read_b128 v[240:243], v177 offset:56320
	global_load_lds_dwordx4 v[174:175], off
	s_add_i32 m0, s0, 0x2000
	s_add_u32 s38, s38, 0x40080
	v_lshl_add_u64 v[174:175], v[190:191], 0, s[52:53]
	s_addc_u32 s39, s39, 0
	s_add_i32 s0, s63, s82
	global_load_lds_dwordx4 v[174:175], off
	v_lshl_add_u64 v[174:175], s[38:39], 0, v[134:135]
	s_mov_b32 m0, s0
	s_nop 0
	global_load_lds_dwordx4 v[174:175], off
	v_lshl_add_u64 v[174:175], s[38:39], 0, v[130:131]
	s_add_i32 m0, s0, 0x2000
	s_nop 0
	global_load_lds_dwordx4 v[174:175], off
	v_lshl_add_u64 v[174:175], v[218:219], 0, s[52:53]
	s_mov_b32 m0, s89
	s_nop 0
	global_load_lds_dwordx4 v[174:175], off
	v_lshl_add_u64 v[174:175], v[244:245], 0, s[52:53]
	s_mov_b32 m0, s90
	s_nop 0
	global_load_lds_dwordx4 v[174:175], off
	s_waitcnt vmcnt(8)
	s_waitcnt lgkmcnt(0)
	s_barrier
	s_setprio 1
	s_waitcnt lgkmcnt(0)
	v_mfma_f32_16x16x32_bf16 v[62:65], v[142:145], v[178:181], v[62:65]
	v_mfma_f32_16x16x32_bf16 v[58:61], v[150:153], v[178:181], v[58:61]
	v_mfma_f32_16x16x32_bf16 v[46:49], v[142:145], v[186:189], v[46:49]
	v_mfma_f32_16x16x32_bf16 v[42:45], v[150:153], v[186:189], v[42:45]
	v_mfma_f32_16x16x32_bf16 v[30:33], v[142:145], v[228:231], v[30:33]
	v_mfma_f32_16x16x32_bf16 v[26:29], v[150:153], v[228:231], v[26:29]
	v_mfma_f32_16x16x32_bf16 v[14:17], v[142:145], v[236:239], v[14:17]
	v_mfma_f32_16x16x32_bf16 v[10:13], v[150:153], v[236:239], v[10:13]
	v_mfma_f32_16x16x32_bf16 v[62:65], v[146:149], v[182:185], v[62:65]
	v_mfma_f32_16x16x32_bf16 v[58:61], v[154:157], v[182:185], v[58:61]
	v_mfma_f32_16x16x32_bf16 v[46:49], v[146:149], v[214:217], v[46:49]
	v_mfma_f32_16x16x32_bf16 v[42:45], v[154:157], v[214:217], v[42:45]
	v_mfma_f32_16x16x32_bf16 v[30:33], v[146:149], v[232:235], v[30:33]
	v_mfma_f32_16x16x32_bf16 v[26:29], v[154:157], v[232:235], v[26:29]
	v_mfma_f32_16x16x32_bf16 v[14:17], v[146:149], v[240:243], v[14:17]
	v_mfma_f32_16x16x32_bf16 v[10:13], v[154:157], v[240:243], v[10:13]
	s_setprio 0
	s_setprio 1
	v_mfma_f32_16x16x32_bf16 v[54:57], v[158:161], v[178:181], v[54:57]
	v_mfma_f32_16x16x32_bf16 v[50:53], v[166:169], v[178:181], v[50:53]
	v_mfma_f32_16x16x32_bf16 v[38:41], v[158:161], v[186:189], v[38:41]
	v_mfma_f32_16x16x32_bf16 v[34:37], v[166:169], v[186:189], v[34:37]
	v_mfma_f32_16x16x32_bf16 v[22:25], v[158:161], v[228:231], v[22:25]
	v_mfma_f32_16x16x32_bf16 v[18:21], v[166:169], v[228:231], v[18:21]
	v_mfma_f32_16x16x32_bf16 v[6:9], v[158:161], v[236:239], v[6:9]
	v_mfma_f32_16x16x32_bf16 v[2:5], v[166:169], v[236:239], v[2:5]
	v_mfma_f32_16x16x32_bf16 v[54:57], v[162:165], v[182:185], v[54:57]
	v_mfma_f32_16x16x32_bf16 v[50:53], v[170:173], v[182:185], v[50:53]
	v_mfma_f32_16x16x32_bf16 v[38:41], v[162:165], v[214:217], v[38:41]
	v_mfma_f32_16x16x32_bf16 v[34:37], v[170:173], v[214:217], v[34:37]
	v_mfma_f32_16x16x32_bf16 v[22:25], v[162:165], v[232:235], v[22:25]
	v_mfma_f32_16x16x32_bf16 v[18:21], v[170:173], v[232:235], v[18:21]
	v_mfma_f32_16x16x32_bf16 v[6:9], v[162:165], v[240:243], v[6:9]
	v_mfma_f32_16x16x32_bf16 v[2:5], v[170:173], v[240:243], v[2:5]
	s_setprio 0
	s_barrier
	s_add_i32 s74, s74, 2
	s_add_u32 s54, s54, 0x100
	s_addc_u32 s55, s55, 0
	s_add_u32 s24, s24, 0x100
	s_addc_u32 s25, s25, 0
	s_cmp_gt_u32 s74, 13
	s_cbranch_scc0 .LBB0_623
	s_and_b64 vcc, exec, s[14:15]
	s_cbranch_vccz .LBB0_626
	s_barrier
.LBB0_626:
	s_lshl_b32 s0, s29, 8
	s_add_i32 s0, s0, s87
	v_and_or_b32 v0, v193, 15, s0
	v_bfe_u32 v142, v193, 4, 2
	s_lshr_b32 s17, s0, 11
	v_and_b32_e32 v143, 0x7ff, v0
	s_cmp_lt_u32 s28, 4
	s_cselect_b32 s0, 0x3e38aa3b, 1.0
	v_add_f32_e32 v194, v195, v194
	v_add_f32_e32 v196, v196, v197
	v_add_f32_e32 v198, v199, v198
	v_add_f32_e32 v200, v200, v201
	v_add_f32_e32 v202, v203, v202
	v_add_f32_e32 v204, v204, v205
	v_add_f32_e32 v206, v207, v206
	v_add_f32_e32 v208, v208, v209
	v_add_f32_e32 v194, v194, v196
	v_add_f32_e32 v198, v198, v200
	v_add_f32_e32 v202, v202, v204
	v_add_f32_e32 v206, v206, v208
	ds_swizzle_b32 v195, v221 offset:swizzle(SWAP,16)
	ds_swizzle_b32 v196, v222 offset:swizzle(SWAP,16)
	ds_swizzle_b32 v199, v223 offset:swizzle(SWAP,16)
	ds_swizzle_b32 v200, v224 offset:swizzle(SWAP,16)
	ds_swizzle_b32 v203, v194 offset:swizzle(SWAP,16)
	ds_swizzle_b32 v204, v198 offset:swizzle(SWAP,16)
	ds_swizzle_b32 v207, v202 offset:swizzle(SWAP,16)
	ds_swizzle_b32 v208, v206 offset:swizzle(SWAP,16)
	s_waitcnt lgkmcnt(0)
	v_add_f32_e32 v221, v221, v195
	v_add_f32_e32 v222, v222, v196
	v_add_f32_e32 v223, v223, v199
	v_add_f32_e32 v224, v224, v200
	v_add_f32_e32 v194, v194, v203
	v_add_f32_e32 v198, v198, v204
	v_add_f32_e32 v202, v202, v207
	v_add_f32_e32 v206, v206, v208
	v_mov_b32_e32 v197, v221
	v_mov_b32_e32 v201, v222
	v_mov_b32_e32 v205, v223
	v_mov_b32_e32 v209, v224
	v_mov_b32_e32 v240, v194
	v_mov_b32_e32 v241, v198
	v_mov_b32_e32 v242, v202
	v_mov_b32_e32 v243, v206
	v_permlane32_swap_b32_e32 v221, v197
	v_permlane32_swap_b32_e32 v222, v201
	v_permlane32_swap_b32_e32 v223, v205
	v_permlane32_swap_b32_e32 v224, v209
	v_permlane32_swap_b32_e32 v194, v240
	v_permlane32_swap_b32_e32 v198, v241
	v_permlane32_swap_b32_e32 v202, v242
	v_permlane32_swap_b32_e32 v206, v243
	v_add_f32_e32 v221, v221, v197
	v_add_f32_e32 v222, v222, v201
	v_add_f32_e32 v223, v223, v205
	v_add_f32_e32 v224, v224, v209
	v_add_f32_e32 v194, v194, v240
	v_add_f32_e32 v198, v198, v241
	v_add_f32_e32 v202, v202, v242
	v_add_f32_e32 v206, v206, v243
	v_fmamk_f32 v221, v221, 0x3a800000, v192
	v_fmamk_f32 v222, v222, 0x3a800000, v192
	v_fmamk_f32 v223, v223, 0x3a800000, v192
	v_fmamk_f32 v224, v224, 0x3a800000, v192
	v_fmamk_f32 v194, v194, 0x3a800000, v192
	v_fmamk_f32 v198, v198, 0x3a800000, v192
	v_fmamk_f32 v202, v202, 0x3a800000, v192
	v_fmamk_f32 v206, v206, 0x3a800000, v192
	v_rsq_f32_e32 v221, v221
	v_rsq_f32_e32 v222, v222
	v_rsq_f32_e32 v223, v223
	v_rsq_f32_e32 v224, v224
	v_rsq_f32_e32 v194, v194
	v_rsq_f32_e32 v198, v198
	v_rsq_f32_e32 v202, v202
	v_rsq_f32_e32 v206, v206
	v_mul_f32_e32 v221, s0, v221
	v_mul_f32_e32 v222, s0, v222
	v_mul_f32_e32 v223, s0, v223
	v_mul_f32_e32 v224, s0, v224
	v_mul_f32_e32 v194, s0, v194
	v_mul_f32_e32 v198, s0, v198
	v_mul_f32_e32 v202, s0, v202
	v_mul_f32_e32 v206, s0, v206
	v_pk_mul_f32 v[126:127], v[126:127], v[220:221] op_sel:[0,1] op_sel_hi:[1,1]
	v_pk_mul_f32 v[128:129], v[128:129], v[220:221] op_sel:[0,1] op_sel_hi:[1,1]
	v_pk_mul_f32 v[122:123], v[122:123], v[220:221] op_sel:[0,1] op_sel_hi:[1,1]
	v_pk_mul_f32 v[124:125], v[124:125], v[220:221] op_sel:[0,1] op_sel_hi:[1,1]
	v_pk_mul_f32 v[118:119], v[118:119], v[220:221] op_sel:[0,1] op_sel_hi:[1,1]
	v_pk_mul_f32 v[120:121], v[120:121], v[220:221] op_sel:[0,1] op_sel_hi:[1,1]
	v_pk_mul_f32 v[114:115], v[114:115], v[220:221] op_sel:[0,1] op_sel_hi:[1,1]
	v_pk_mul_f32 v[116:117], v[116:117], v[220:221] op_sel:[0,1] op_sel_hi:[1,1]
	v_pk_mul_f32 v[110:111], v[110:111], v[222:223] op_sel_hi:[1,0]
	v_pk_mul_f32 v[112:113], v[112:113], v[222:223] op_sel_hi:[1,0]
	v_pk_mul_f32 v[106:107], v[106:107], v[222:223] op_sel_hi:[1,0]
	v_pk_mul_f32 v[108:109], v[108:109], v[222:223] op_sel_hi:[1,0]
	v_pk_mul_f32 v[102:103], v[102:103], v[222:223] op_sel_hi:[1,0]
	v_pk_mul_f32 v[104:105], v[104:105], v[222:223] op_sel_hi:[1,0]
	v_pk_mul_f32 v[98:99], v[98:99], v[222:223] op_sel_hi:[1,0]
	v_pk_mul_f32 v[100:101], v[100:101], v[222:223] op_sel_hi:[1,0]
	v_pk_mul_f32 v[94:95], v[94:95], v[222:223] op_sel:[0,1] op_sel_hi:[1,1]
	v_pk_mul_f32 v[96:97], v[96:97], v[222:223] op_sel:[0,1] op_sel_hi:[1,1]
	v_pk_mul_f32 v[90:91], v[90:91], v[222:223] op_sel:[0,1] op_sel_hi:[1,1]
	v_pk_mul_f32 v[92:93], v[92:93], v[222:223] op_sel:[0,1] op_sel_hi:[1,1]
	v_pk_mul_f32 v[86:87], v[86:87], v[222:223] op_sel:[0,1] op_sel_hi:[1,1]
	v_pk_mul_f32 v[88:89], v[88:89], v[222:223] op_sel:[0,1] op_sel_hi:[1,1]
	v_pk_mul_f32 v[82:83], v[82:83], v[222:223] op_sel:[0,1] op_sel_hi:[1,1]
	v_pk_mul_f32 v[84:85], v[84:85], v[222:223] op_sel:[0,1] op_sel_hi:[1,1]
	v_pk_mul_f32 v[78:79], v[78:79], v[224:225] op_sel_hi:[1,0]
	v_pk_mul_f32 v[80:81], v[80:81], v[224:225] op_sel_hi:[1,0]
	v_pk_mul_f32 v[74:75], v[74:75], v[224:225] op_sel_hi:[1,0]
	v_pk_mul_f32 v[76:77], v[76:77], v[224:225] op_sel_hi:[1,0]
	v_pk_mul_f32 v[70:71], v[70:71], v[224:225] op_sel_hi:[1,0]
	v_pk_mul_f32 v[72:73], v[72:73], v[224:225] op_sel_hi:[1,0]
	v_pk_mul_f32 v[66:67], v[66:67], v[224:225] op_sel_hi:[1,0]
	v_pk_mul_f32 v[68:69], v[68:69], v[224:225] op_sel_hi:[1,0]
	v_pk_mul_f32 v[62:63], v[62:63], v[194:195] op_sel_hi:[1,0]
	v_pk_mul_f32 v[64:65], v[64:65], v[194:195] op_sel_hi:[1,0]
	v_pk_mul_f32 v[58:59], v[58:59], v[194:195] op_sel_hi:[1,0]
	v_pk_mul_f32 v[60:61], v[60:61], v[194:195] op_sel_hi:[1,0]
	v_pk_mul_f32 v[54:55], v[54:55], v[194:195] op_sel_hi:[1,0]
	v_pk_mul_f32 v[56:57], v[56:57], v[194:195] op_sel_hi:[1,0]
	v_pk_mul_f32 v[50:51], v[50:51], v[194:195] op_sel_hi:[1,0]
	v_pk_mul_f32 v[52:53], v[52:53], v[194:195] op_sel_hi:[1,0]
	v_pk_mul_f32 v[46:47], v[46:47], v[198:199] op_sel_hi:[1,0]
	v_pk_mul_f32 v[48:49], v[48:49], v[198:199] op_sel_hi:[1,0]
	v_pk_mul_f32 v[42:43], v[42:43], v[198:199] op_sel_hi:[1,0]
	v_pk_mul_f32 v[44:45], v[44:45], v[198:199] op_sel_hi:[1,0]
	v_pk_mul_f32 v[38:39], v[38:39], v[198:199] op_sel_hi:[1,0]
	v_pk_mul_f32 v[40:41], v[40:41], v[198:199] op_sel_hi:[1,0]
	v_pk_mul_f32 v[34:35], v[34:35], v[198:199] op_sel_hi:[1,0]
	v_pk_mul_f32 v[36:37], v[36:37], v[198:199] op_sel_hi:[1,0]
	v_pk_mul_f32 v[30:31], v[30:31], v[202:203] op_sel_hi:[1,0]
	v_pk_mul_f32 v[32:33], v[32:33], v[202:203] op_sel_hi:[1,0]
	v_pk_mul_f32 v[26:27], v[26:27], v[202:203] op_sel_hi:[1,0]
	v_pk_mul_f32 v[28:29], v[28:29], v[202:203] op_sel_hi:[1,0]
	v_pk_mul_f32 v[22:23], v[22:23], v[202:203] op_sel_hi:[1,0]
	v_pk_mul_f32 v[24:25], v[24:25], v[202:203] op_sel_hi:[1,0]
	v_pk_mul_f32 v[18:19], v[18:19], v[202:203] op_sel_hi:[1,0]
	v_pk_mul_f32 v[20:21], v[20:21], v[202:203] op_sel_hi:[1,0]
	v_pk_mul_f32 v[14:15], v[14:15], v[206:207] op_sel_hi:[1,0]
	v_pk_mul_f32 v[16:17], v[16:17], v[206:207] op_sel_hi:[1,0]
	v_pk_mul_f32 v[10:11], v[10:11], v[206:207] op_sel_hi:[1,0]
	v_pk_mul_f32 v[12:13], v[12:13], v[206:207] op_sel_hi:[1,0]
	v_pk_mul_f32 v[6:7], v[6:7], v[206:207] op_sel_hi:[1,0]
	v_pk_mul_f32 v[8:9], v[8:9], v[206:207] op_sel_hi:[1,0]
	v_pk_mul_f32 v[2:3], v[2:3], v[206:207] op_sel_hi:[1,0]
	v_pk_mul_f32 v[4:5], v[4:5], v[206:207] op_sel_hi:[1,0]
	s_lshr_b32 s38, s88, 5
	s_cmp_lt_u32 s28, 4
	s_cbranch_scc0 .Lqkv_kv
	s_lshl_b32 s39, s28, 9
	s_lshl_b32 s38, s88, 1
	s_or_b32 s39, s39, s38
	v_lshl_or_b32 v148, v142, 4, s39
	v_mad_u32_u24 v144, v0, s47, v148
	v_cvt_pk_bf16_f32 v126, v126, v127
	v_cvt_pk_bf16_f32 v127, v128, v129
	v_cvt_pk_bf16_f32 v128, v122, v123
	v_cvt_pk_bf16_f32 v129, v124, v125
	v_add_u32_e32 v145, 0x0, v144
	global_store_dwordx4 v145, v[126:129], s[6:7]
	v_cvt_pk_bf16_f32 v118, v118, v119
	v_cvt_pk_bf16_f32 v119, v120, v121
	v_cvt_pk_bf16_f32 v120, v114, v115
	v_cvt_pk_bf16_f32 v121, v116, v117
	v_add_u32_e32 v146, 0x0, v144
	global_store_dwordx4 v146, v[118:121], s[6:7] offset:256
	v_cvt_pk_bf16_f32 v110, v110, v111
	v_cvt_pk_bf16_f32 v111, v112, v113
	v_cvt_pk_bf16_f32 v112, v106, v107
	v_cvt_pk_bf16_f32 v113, v108, v109
	v_add_u32_e32 v145, 0xc000, v144
	global_store_dwordx4 v145, v[110:113], s[6:7]
	v_cvt_pk_bf16_f32 v102, v102, v103
	v_cvt_pk_bf16_f32 v103, v104, v105
	v_cvt_pk_bf16_f32 v104, v98, v99
	v_cvt_pk_bf16_f32 v105, v100, v101
	v_add_u32_e32 v146, 0xc000, v144
	global_store_dwordx4 v146, v[102:105], s[6:7] offset:256
	v_cvt_pk_bf16_f32 v94, v94, v95
	v_cvt_pk_bf16_f32 v95, v96, v97
	v_cvt_pk_bf16_f32 v96, v90, v91
	v_cvt_pk_bf16_f32 v97, v92, v93
	v_add_u32_e32 v145, 0x18000, v144
	global_store_dwordx4 v145, v[94:97], s[6:7]
	v_cvt_pk_bf16_f32 v86, v86, v87
	v_cvt_pk_bf16_f32 v87, v88, v89
	v_cvt_pk_bf16_f32 v88, v82, v83
	v_cvt_pk_bf16_f32 v89, v84, v85
	v_add_u32_e32 v146, 0x18000, v144
	global_store_dwordx4 v146, v[86:89], s[6:7] offset:256
	v_cvt_pk_bf16_f32 v78, v78, v79
	v_cvt_pk_bf16_f32 v79, v80, v81
	v_cvt_pk_bf16_f32 v80, v74, v75
	v_cvt_pk_bf16_f32 v81, v76, v77
	v_add_u32_e32 v145, 0x24000, v144
	global_store_dwordx4 v145, v[78:81], s[6:7]
	v_cvt_pk_bf16_f32 v70, v70, v71
	v_cvt_pk_bf16_f32 v71, v72, v73
	v_cvt_pk_bf16_f32 v72, v66, v67
	v_cvt_pk_bf16_f32 v73, v68, v69
	v_add_u32_e32 v146, 0x24000, v144
	global_store_dwordx4 v146, v[70:73], s[6:7] offset:256
	v_cvt_pk_bf16_f32 v62, v62, v63
	v_cvt_pk_bf16_f32 v63, v64, v65
	v_cvt_pk_bf16_f32 v64, v58, v59
	v_cvt_pk_bf16_f32 v65, v60, v61
	v_add_u32_e32 v145, 0x60000, v144
	global_store_dwordx4 v145, v[62:65], s[6:7]
	v_cvt_pk_bf16_f32 v54, v54, v55
	v_cvt_pk_bf16_f32 v55, v56, v57
	v_cvt_pk_bf16_f32 v56, v50, v51
	v_cvt_pk_bf16_f32 v57, v52, v53
	v_add_u32_e32 v146, 0x60000, v144
	global_store_dwordx4 v146, v[54:57], s[6:7] offset:256
	v_cvt_pk_bf16_f32 v46, v46, v47
	v_cvt_pk_bf16_f32 v47, v48, v49
	v_cvt_pk_bf16_f32 v48, v42, v43
	v_cvt_pk_bf16_f32 v49, v44, v45
	v_add_u32_e32 v145, 0x6c000, v144
	global_store_dwordx4 v145, v[46:49], s[6:7]
	v_cvt_pk_bf16_f32 v38, v38, v39
	v_cvt_pk_bf16_f32 v39, v40, v41
	v_cvt_pk_bf16_f32 v40, v34, v35
	v_cvt_pk_bf16_f32 v41, v36, v37
	v_add_u32_e32 v146, 0x6c000, v144
	global_store_dwordx4 v146, v[38:41], s[6:7] offset:256
	v_cvt_pk_bf16_f32 v30, v30, v31
	v_cvt_pk_bf16_f32 v31, v32, v33
	v_cvt_pk_bf16_f32 v32, v26, v27
	v_cvt_pk_bf16_f32 v33, v28, v29
	v_add_u32_e32 v145, 0x78000, v144
	global_store_dwordx4 v145, v[30:33], s[6:7]
	v_cvt_pk_bf16_f32 v22, v22, v23
	v_cvt_pk_bf16_f32 v23, v24, v25
	v_cvt_pk_bf16_f32 v24, v18, v19
	v_cvt_pk_bf16_f32 v25, v20, v21
	v_add_u32_e32 v146, 0x78000, v144
	global_store_dwordx4 v146, v[22:25], s[6:7] offset:256
	v_cvt_pk_bf16_f32 v14, v14, v15
	v_cvt_pk_bf16_f32 v15, v16, v17
	v_cvt_pk_bf16_f32 v16, v10, v11
	v_cvt_pk_bf16_f32 v17, v12, v13
	v_add_u32_e32 v145, 0x84000, v144
	global_store_dwordx4 v145, v[14:17], s[6:7]
	v_cvt_pk_bf16_f32 v6, v6, v7
	v_cvt_pk_bf16_f32 v7, v8, v9
	v_cvt_pk_bf16_f32 v8, v2, v3
	v_cvt_pk_bf16_f32 v9, v4, v5
	v_add_u32_e32 v146, 0x84000, v144
	global_store_dwordx4 v146, v[6:9], s[6:7] offset:256
	s_branch .Lqkv_end
.Lqkv_kv:
	s_cmp_eq_u32 s28, 4
	s_cbranch_scc0 .Lqkv_v
	s_lshl_b32 s39, s17, 5
	s_lshl_b32 s38, s38, 2
	s_add_i32 s39, s39, s38
	v_add_u32_e32 v148, s39, v142
	v_lshlrev_b32_e32 v148, 15, v148
	v_lshl_add_u32 v144, v143, 4, v148
	v_add_u32_e32 v145, 0x80000, v144
	v_cvt_pk_bf16_f32 v126, v126, v127
	v_cvt_pk_bf16_f32 v127, v128, v129
	v_cvt_pk_bf16_f32 v128, v122, v123
	v_cvt_pk_bf16_f32 v129, v124, v125
	global_store_dwordx4 v144, v[126:129], s[8:9]
	v_cvt_pk_bf16_f32 v118, v118, v119
	v_cvt_pk_bf16_f32 v119, v120, v121
	v_cvt_pk_bf16_f32 v120, v114, v115
	v_cvt_pk_bf16_f32 v121, v116, v117
	global_store_dwordx4 v145, v[118:121], s[8:9]
	v_cvt_pk_bf16_f32 v110, v110, v111
	v_cvt_pk_bf16_f32 v111, v112, v113
	v_cvt_pk_bf16_f32 v112, v106, v107
	v_cvt_pk_bf16_f32 v113, v108, v109
	global_store_dwordx4 v144, v[110:113], s[8:9] offset:256
	v_cvt_pk_bf16_f32 v102, v102, v103
	v_cvt_pk_bf16_f32 v103, v104, v105
	v_cvt_pk_bf16_f32 v104, v98, v99
	v_cvt_pk_bf16_f32 v105, v100, v101
	global_store_dwordx4 v145, v[102:105], s[8:9] offset:256
	v_cvt_pk_bf16_f32 v94, v94, v95
	v_cvt_pk_bf16_f32 v95, v96, v97
	v_cvt_pk_bf16_f32 v96, v90, v91
	v_cvt_pk_bf16_f32 v97, v92, v93
	global_store_dwordx4 v144, v[94:97], s[8:9] offset:512
	v_cvt_pk_bf16_f32 v86, v86, v87
	v_cvt_pk_bf16_f32 v87, v88, v89
	v_cvt_pk_bf16_f32 v88, v82, v83
	v_cvt_pk_bf16_f32 v89, v84, v85
	global_store_dwordx4 v145, v[86:89], s[8:9] offset:512
	v_cvt_pk_bf16_f32 v78, v78, v79
	v_cvt_pk_bf16_f32 v79, v80, v81
	v_cvt_pk_bf16_f32 v80, v74, v75
	v_cvt_pk_bf16_f32 v81, v76, v77
	global_store_dwordx4 v144, v[78:81], s[8:9] offset:768
	v_cvt_pk_bf16_f32 v70, v70, v71
	v_cvt_pk_bf16_f32 v71, v72, v73
	v_cvt_pk_bf16_f32 v72, v66, v67
	v_cvt_pk_bf16_f32 v73, v68, v69
	global_store_dwordx4 v145, v[70:73], s[8:9] offset:768
	v_cvt_pk_bf16_f32 v62, v62, v63
	v_cvt_pk_bf16_f32 v63, v64, v65
	v_cvt_pk_bf16_f32 v64, v58, v59
	v_cvt_pk_bf16_f32 v65, v60, v61
	global_store_dwordx4 v144, v[62:65], s[8:9] offset:2048
	v_cvt_pk_bf16_f32 v54, v54, v55
	v_cvt_pk_bf16_f32 v55, v56, v57
	v_cvt_pk_bf16_f32 v56, v50, v51
	v_cvt_pk_bf16_f32 v57, v52, v53
	global_store_dwordx4 v145, v[54:57], s[8:9] offset:2048
	v_cvt_pk_bf16_f32 v46, v46, v47
	v_cvt_pk_bf16_f32 v47, v48, v49
	v_cvt_pk_bf16_f32 v48, v42, v43
	v_cvt_pk_bf16_f32 v49, v44, v45
	global_store_dwordx4 v144, v[46:49], s[8:9] offset:2304
	v_cvt_pk_bf16_f32 v38, v38, v39
	v_cvt_pk_bf16_f32 v39, v40, v41
	v_cvt_pk_bf16_f32 v40, v34, v35
	v_cvt_pk_bf16_f32 v41, v36, v37
	global_store_dwordx4 v145, v[38:41], s[8:9] offset:2304
	v_cvt_pk_bf16_f32 v30, v30, v31
	v_cvt_pk_bf16_f32 v31, v32, v33
	v_cvt_pk_bf16_f32 v32, v26, v27
	v_cvt_pk_bf16_f32 v33, v28, v29
	global_store_dwordx4 v144, v[30:33], s[8:9] offset:2560
	v_cvt_pk_bf16_f32 v22, v22, v23
	v_cvt_pk_bf16_f32 v23, v24, v25
	v_cvt_pk_bf16_f32 v24, v18, v19
	v_cvt_pk_bf16_f32 v25, v20, v21
	global_store_dwordx4 v145, v[22:25], s[8:9] offset:2560
	v_cvt_pk_bf16_f32 v14, v14, v15
	v_cvt_pk_bf16_f32 v15, v16, v17
	v_cvt_pk_bf16_f32 v16, v10, v11
	v_cvt_pk_bf16_f32 v17, v12, v13
	global_store_dwordx4 v144, v[14:17], s[8:9] offset:2816
	v_cvt_pk_bf16_f32 v6, v6, v7
	v_cvt_pk_bf16_f32 v7, v8, v9
	v_cvt_pk_bf16_f32 v8, v2, v3
	v_cvt_pk_bf16_f32 v9, v4, v5
	global_store_dwordx4 v145, v[6:9], s[8:9] offset:2816
	s_branch .Lqkv_end
.Lqkv_v:
	s_lshl_b32 s39, s17, 3
	s_add_i32 s39, s39, s38
	s_lshl_b32 s39, s39, 17
	v_lshlrev_b32_e32 v148, 4, v142
	v_lshl_add_u32 v148, v143, 6, v148
	v_add_u32_e32 v144, s39, v148
	v_add_u32_e32 v145, 0x80000, v144
	v_add_u32_e32 v146, 0x2000, v144
	v_add_u32_e32 v147, 0x82000, v144
	v_cvt_pk_bf16_f32 v126, v126, v127
	v_cvt_pk_bf16_f32 v127, v128, v129
	v_cvt_pk_bf16_f32 v128, v122, v123
	v_cvt_pk_bf16_f32 v129, v124, v125
	global_store_dwordx4 v144, v[126:129], s[10:11]
	v_cvt_pk_bf16_f32 v118, v118, v119
	v_cvt_pk_bf16_f32 v119, v120, v121
	v_cvt_pk_bf16_f32 v120, v114, v115
	v_cvt_pk_bf16_f32 v121, v116, v117
	global_store_dwordx4 v145, v[118:121], s[10:11]
	v_cvt_pk_bf16_f32 v110, v110, v111
	v_cvt_pk_bf16_f32 v111, v112, v113
	v_cvt_pk_bf16_f32 v112, v106, v107
	v_cvt_pk_bf16_f32 v113, v108, v109
	global_store_dwordx4 v144, v[110:113], s[10:11] offset:1024
	v_cvt_pk_bf16_f32 v102, v102, v103
	v_cvt_pk_bf16_f32 v103, v104, v105
	v_cvt_pk_bf16_f32 v104, v98, v99
	v_cvt_pk_bf16_f32 v105, v100, v101
	global_store_dwordx4 v145, v[102:105], s[10:11] offset:1024
	v_cvt_pk_bf16_f32 v94, v94, v95
	v_cvt_pk_bf16_f32 v95, v96, v97
	v_cvt_pk_bf16_f32 v96, v90, v91
	v_cvt_pk_bf16_f32 v97, v92, v93
	global_store_dwordx4 v144, v[94:97], s[10:11] offset:2048
	v_cvt_pk_bf16_f32 v86, v86, v87
	v_cvt_pk_bf16_f32 v87, v88, v89
	v_cvt_pk_bf16_f32 v88, v82, v83
	v_cvt_pk_bf16_f32 v89, v84, v85
	global_store_dwordx4 v145, v[86:89], s[10:11] offset:2048
	v_cvt_pk_bf16_f32 v78, v78, v79
	v_cvt_pk_bf16_f32 v79, v80, v81
	v_cvt_pk_bf16_f32 v80, v74, v75
	v_cvt_pk_bf16_f32 v81, v76, v77
	global_store_dwordx4 v144, v[78:81], s[10:11] offset:3072
	v_cvt_pk_bf16_f32 v70, v70, v71
	v_cvt_pk_bf16_f32 v71, v72, v73
	v_cvt_pk_bf16_f32 v72, v66, v67
	v_cvt_pk_bf16_f32 v73, v68, v69
	global_store_dwordx4 v145, v[70:73], s[10:11] offset:3072
	v_cvt_pk_bf16_f32 v62, v62, v63
	v_cvt_pk_bf16_f32 v63, v64, v65
	v_cvt_pk_bf16_f32 v64, v58, v59
	v_cvt_pk_bf16_f32 v65, v60, v61
	global_store_dwordx4 v146, v[62:65], s[10:11]
	v_cvt_pk_bf16_f32 v54, v54, v55
	v_cvt_pk_bf16_f32 v55, v56, v57
	v_cvt_pk_bf16_f32 v56, v50, v51
	v_cvt_pk_bf16_f32 v57, v52, v53
	global_store_dwordx4 v147, v[54:57], s[10:11]
	v_cvt_pk_bf16_f32 v46, v46, v47
	v_cvt_pk_bf16_f32 v47, v48, v49
	v_cvt_pk_bf16_f32 v48, v42, v43
	v_cvt_pk_bf16_f32 v49, v44, v45
	global_store_dwordx4 v146, v[46:49], s[10:11] offset:1024
	v_cvt_pk_bf16_f32 v38, v38, v39
	v_cvt_pk_bf16_f32 v39, v40, v41
	v_cvt_pk_bf16_f32 v40, v34, v35
	v_cvt_pk_bf16_f32 v41, v36, v37
	global_store_dwordx4 v147, v[38:41], s[10:11] offset:1024
	v_cvt_pk_bf16_f32 v30, v30, v31
	v_cvt_pk_bf16_f32 v31, v32, v33
	v_cvt_pk_bf16_f32 v32, v26, v27
	v_cvt_pk_bf16_f32 v33, v28, v29
	global_store_dwordx4 v146, v[30:33], s[10:11] offset:2048
	v_cvt_pk_bf16_f32 v22, v22, v23
	v_cvt_pk_bf16_f32 v23, v24, v25
	v_cvt_pk_bf16_f32 v24, v18, v19
	v_cvt_pk_bf16_f32 v25, v20, v21
	global_store_dwordx4 v147, v[22:25], s[10:11] offset:2048
	v_cvt_pk_bf16_f32 v14, v14, v15
	v_cvt_pk_bf16_f32 v15, v16, v17
	v_cvt_pk_bf16_f32 v16, v10, v11
	v_cvt_pk_bf16_f32 v17, v12, v13
	global_store_dwordx4 v146, v[14:17], s[10:11] offset:3072
	v_cvt_pk_bf16_f32 v6, v6, v7
	v_cvt_pk_bf16_f32 v7, v8, v9
	v_cvt_pk_bf16_f32 v8, v2, v3
	v_cvt_pk_bf16_f32 v9, v4, v5
	global_store_dwordx4 v147, v[6:9], s[10:11] offset:3072
.Lqkv_end:
	v_mov_b64_e32 v[194:195], 0xc0
	v_mov_b64_e32 v[196:197], 0xbf
	v_mov_b64_e32 v[198:199], 0x180
	v_mov_b64_e32 v[200:201], 0x17f
	v_mov_b64_e32 v[202:203], 0x200
	v_mov_b64_e32 v[204:205], 0x1ff
	v_mov_b64_e32 v[206:207], 0x100
	v_mov_b64_e32 v[208:209], 0xff
	v_mov_b32_e32 v221, 0x3e38aa3b
	v_mov_b32_e32 v222, 0x7c
	v_mov_b32_e32 v223, 0x80
	v_mov_b32_e32 v224, 0x42800000
	s_andn2_b64 vcc, exec, s[36:37]
	s_mov_b64 s[24:25], -1
	s_cbranch_vccnz .LBB0_619
	s_andn2_b64 vcc, exec, s[2:3]
	s_cbranch_vccnz .LBB0_618
	s_barrier
	s_branch .LBB0_618

.LBB0_1103:
	s_add_u32 s0, s2, 0xfffc0080
	s_addc_u32 s24, s3, -1
	s_add_i32 s30, 0, 0x10000
	s_cmp_eq_u32 s83, 12
	s_cselect_b32 s43, s17, s24
	s_cselect_b32 s42, s54, s0
	v_add_u32_e32 v0, s30, v178
	s_cselect_b32 s25, s15, s82
	s_cselect_b32 s24, s55, s71
	s_add_i32 s0, 0, 0x14000
	ds_read_b128 v[130:133], v0
	ds_read_b128 v[146:149], v0 offset:1024
	ds_read_b128 v[150:153], v0 offset:2048
	ds_read_b128 v[154:157], v0 offset:3072
	v_add_u32_e32 v0, s0, v178
	ds_read_b128 v[158:161], v0
	ds_read_b128 v[162:165], v0 offset:1024
	ds_read_b128 v[166:169], v0 offset:2048
	ds_read_b128 v[170:173], v0 offset:3072
	s_cmp_eq_u32 s83, 12
	s_cbranch_scc0 .Lgu_pa_skip
	v_and_b32_e32 v253, 15, v193
	v_lshl_add_u32 v252, s29, 8, v253
	v_add_u32_e32 v252, s77, v252
	v_bfe_u32 v253, v193, 4, 2
	v_lshlrev_b32_e32 v252, 6, v252
	v_lshl_add_u32 v252, v253, 4, v252
	global_load_dwordx4 v[194:197], v252, s[10:11]
	global_load_dwordx4 v[198:201], v252, s[10:11] offset:1024
	global_load_dwordx4 v[202:205], v252, s[10:11] offset:2048
	global_load_dwordx4 v[206:209], v252, s[10:11] offset:3072
